# H2 + scan2: counted vmcnt(24) instead of per-iteration vmcnt(0) drain (prefetch of the second chunk set stays in flight)
# baseline (speedup 1.0000x reference)
; template <bool OUT> ...
;     const int tid = threadIdx.x, lane = tid & 63, w = __builtin_amdgcn_readfirstlane(tid >> 6), fr = lane & 15, q = lane >> 4;
;     float* PART = (float*)(lds + L_PART); float* ER = (float*)(lds + L_ER); float* EBR = (float*)(lds + L_EBR);
;     {
;         f32x2 kf[8], loc[8]; f32x2 run = {1.f, 1.f};
; #pragma unroll
;         for (int j = 0; j < 8; ++j) { const h16x2 kk = __builtin_bit_cast(h16x2, gk[j]); kf[j] = (f32x2){(float)kk.x, (float)kk.y}; }
;         if (w >= 4) {
; #pragma unroll
;             for (int j = 0; j < 8; ++j) { run *= 1.f - kf[j]; loc[j] = run; }
;         } else {
; #pragma unroll
;             for (int j = 7; j >= 0; --j) { loc[j] = run; run *= 1.f - kf[j]; }
;         }
.LBB0_470:
	s_waitcnt vmcnt(24)
	v_cvt_f32_f16_sdwa v73, v95 dst_sel:DWORD dst_unused:UNUSED_PAD src0_sel:WORD_1
	v_cvt_f32_f16_e32 v72, v95
	v_cvt_f32_f16_sdwa v69, v159 dst_sel:DWORD dst_unused:UNUSED_PAD src0_sel:WORD_1
	v_cvt_f32_f16_e32 v68, v159
	v_cvt_f32_f16_sdwa v65, v162 dst_sel:DWORD dst_unused:UNUSED_PAD src0_sel:WORD_1
	v_cvt_f32_f16_e32 v64, v162
	v_cvt_f32_f16_sdwa v59, v165 dst_sel:DWORD dst_unused:UNUSED_PAD src0_sel:WORD_1
	v_cvt_f32_f16_e32 v58, v165
	v_cvt_f32_f16_sdwa v57, v168 dst_sel:DWORD dst_unused:UNUSED_PAD src0_sel:WORD_1
	v_cvt_f32_f16_e32 v56, v168
	v_cvt_f32_f16_sdwa v53, v171 dst_sel:DWORD dst_unused:UNUSED_PAD src0_sel:WORD_1
	v_cvt_f32_f16_e32 v52, v171
	v_cvt_f32_f16_sdwa v51, v182 dst_sel:DWORD dst_unused:UNUSED_PAD src0_sel:WORD_1
	v_cvt_f32_f16_e32 v50, v182
	v_cvt_f32_f16_sdwa v49, v185 dst_sel:DWORD dst_unused:UNUSED_PAD src0_sel:WORD_1
	v_cvt_f32_f16_e32 v48, v185
	v_readfirstlane_b32 s0, v242
	s_cmpk_gt_u32 s0, 0xff
	s_cselect_b64 s[2:3], -1, 0
	s_mov_b64 s[8:9], -1
	s_and_b64 vcc, exec, s[2:3]
	v_pk_add_f32 v[54:55], v[48:49], 1.0 op_sel_hi:[1,0] neg_lo:[1,0] neg_hi:[1,0]
	v_pk_add_f32 v[2:3], v[50:51], 1.0 op_sel_hi:[1,0] neg_lo:[1,0] neg_hi:[1,0]
	v_pk_add_f32 v[4:5], v[52:53], 1.0 op_sel_hi:[1,0] neg_lo:[1,0] neg_hi:[1,0]
	v_pk_add_f32 v[8:9], v[56:57], 1.0 op_sel_hi:[1,0] neg_lo:[1,0] neg_hi:[1,0]
	v_pk_add_f32 v[10:11], v[58:59], 1.0 op_sel_hi:[1,0] neg_lo:[1,0] neg_hi:[1,0]
	v_pk_add_f32 v[12:13], v[64:65], 1.0 op_sel_hi:[1,0] neg_lo:[1,0] neg_hi:[1,0]
	v_pk_add_f32 v[14:15], v[68:69], 1.0 op_sel_hi:[1,0] neg_lo:[1,0] neg_hi:[1,0]
	v_pk_add_f32 v[6:7], v[72:73], 1.0 op_sel_hi:[1,0] neg_lo:[1,0] neg_hi:[1,0]
	s_cbranch_vccnz .LBB0_472
	v_pk_mul_f32 v[60:61], v[54:55], v[2:3]
	v_pk_add_f32 v[0:1], v[72:73], 1.0 op_sel_hi:[1,0] neg_lo:[1,0] neg_hi:[1,0]
	v_pk_mul_f32 v[66:67], v[4:5], v[60:61]
	s_mov_b64 s[8:9], 0
	v_pk_mul_f32 v[70:71], v[8:9], v[66:67]
	s_nop 0
	v_pk_mul_f32 v[74:75], v[10:11], v[70:71]
	s_nop 0
	v_pk_mul_f32 v[76:77], v[12:13], v[74:75]
	s_nop 0
	v_pk_mul_f32 v[78:79], v[14:15], v[76:77]
	s_nop 0
	v_pk_mul_f32 v[0:1], v[0:1], v[78:79]

; #define SCAN_LOADB(GK, VV, QQ, c) do { _Pragma("unroll") for (int j = 0; j < 8; ++j) { const size_t row = (size_t)(r0 + rs * (64 * (c) + 8 * w + j)); \
;         GK[j] = *(const unsigned*)(Gp + row * 2048 + gcol + 2 * lane); VV[j] = *(const unsigned*)(Vp + row * 1024 + hcol + 2 * lane); if (OUT) QQ[j] = *(const unsigned*)(Qp + row * 1024 + hcol + 2 * lane); } } while (0)
; template <bool OUT> ...
;     ...
;         if (cpre >= 0) SCAN_LOADB(gk, vv, qq, cpre);
.LBB0_476:
	s_add_i32 s71, s72, 2
	s_cmp_ge_u32 s71, s68
	s_cselect_b64 s[8:9], -1, 0
	s_cmp_lt_u32 s71, s68
	s_cselect_b32 s3, s71, -1
	s_cmp_lt_i32 s3, 0
	s_cbranch_scc1 .Lscan2_skip_refill
	s_lshl_b32 s10, s20, 3
	s_lshl_b32 s3, s3, 6
	s_add_i32 s3, s3, s10
	s_mul_i32 s3, s3, s66
	s_add_i32 s10, s3, s67
	s_ashr_i32 s11, s10, 31
	s_lshl_b64 s[74:75], s[10:11], 12
	v_lshl_add_u64 v[0:1], v[106:107], 0, s[74:75]
	s_lshl_b64 s[74:75], s[10:11], 11
	s_add_i32 s10, s10, s66
	s_ashr_i32 s11, s10, 31
	v_lshl_add_u64 v[2:3], v[108:109], 0, s[74:75]
	v_lshl_add_u64 v[4:5], v[110:111], 0, s[74:75]
	s_lshl_b64 s[74:75], s[10:11], 12
	v_lshl_add_u64 v[6:7], v[106:107], 0, s[74:75]
	s_lshl_b64 s[74:75], s[10:11], 11
	s_add_i32 s10, s10, s66
	s_ashr_i32 s11, s10, 31
	v_lshl_add_u64 v[8:9], v[108:109], 0, s[74:75]
	v_lshl_add_u64 v[10:11], v[110:111], 0, s[74:75]
	s_lshl_b64 s[74:75], s[10:11], 12
	v_lshl_add_u64 v[12:13], v[106:107], 0, s[74:75]
	s_lshl_b64 s[74:75], s[10:11], 11
	s_add_i32 s10, s10, s66
	s_ashr_i32 s11, s10, 31
	v_lshl_add_u64 v[14:15], v[108:109], 0, s[74:75]
	global_load_dword v95, v[0:1], off
	global_load_dword v157, v[2:3], off
	global_load_dword v158, v[4:5], off
	global_load_dword v159, v[6:7], off
	global_load_dword v160, v[8:9], off
	global_load_dword v161, v[10:11], off
	global_load_dword v162, v[12:13], off
	global_load_dword v163, v[14:15], off
	v_lshl_add_u64 v[0:1], v[110:111], 0, s[74:75]
	s_lshl_b64 s[74:75], s[10:11], 12
	v_lshl_add_u64 v[2:3], v[106:107], 0, s[74:75]
	s_lshl_b64 s[74:75], s[10:11], 11
	s_add_i32 s10, s10, s66
	s_ashr_i32 s11, s10, 31
	v_lshl_add_u64 v[4:5], v[108:109], 0, s[74:75]
	v_lshl_add_u64 v[6:7], v[110:111], 0, s[74:75]
	s_lshl_b64 s[74:75], s[10:11], 12
	v_lshl_add_u64 v[8:9], v[106:107], 0, s[74:75]
	s_lshl_b64 s[74:75], s[10:11], 11
	s_add_i32 s10, s10, s66
	s_ashr_i32 s11, s10, 31
	v_lshl_add_u64 v[10:11], v[108:109], 0, s[74:75]
	v_lshl_add_u64 v[12:13], v[110:111], 0, s[74:75]
	s_lshl_b64 s[74:75], s[10:11], 12
	v_lshl_add_u64 v[14:15], v[106:107], 0, s[74:75]
	s_lshl_b64 s[74:75], s[10:11], 11
	s_add_i32 s10, s10, s66
	s_ashr_i32 s11, s10, 31
	global_load_dword v164, v[0:1], off
	global_load_dword v165, v[2:3], off
	global_load_dword v166, v[4:5], off
	global_load_dword v167, v[6:7], off
	global_load_dword v168, v[8:9], off
	global_load_dword v169, v[10:11], off
	global_load_dword v170, v[12:13], off
	global_load_dword v171, v[14:15], off
	v_lshl_add_u64 v[0:1], v[108:109], 0, s[74:75]
	v_lshl_add_u64 v[2:3], v[110:111], 0, s[74:75]
	s_lshl_b64 s[74:75], s[10:11], 12
	v_lshl_add_u64 v[4:5], v[106:107], 0, s[74:75]
	s_lshl_b64 s[74:75], s[10:11], 11
	s_add_i32 s10, s10, s66
	s_ashr_i32 s11, s10, 31
	v_lshl_add_u64 v[6:7], v[108:109], 0, s[74:75]
	v_lshl_add_u64 v[8:9], v[110:111], 0, s[74:75]
	s_lshl_b64 s[74:75], s[10:11], 12
	s_lshl_b64 s[10:11], s[10:11], 11
	v_lshl_add_u64 v[10:11], v[106:107], 0, s[74:75]
	v_lshl_add_u64 v[12:13], v[108:109], 0, s[10:11]
	v_lshl_add_u64 v[14:15], v[110:111], 0, s[10:11]
	global_load_dword v180, v[0:1], off
	global_load_dword v181, v[2:3], off
	global_load_dword v182, v[4:5], off
	global_load_dword v183, v[6:7], off
	global_load_dword v184, v[8:9], off
	global_load_dword v185, v[10:11], off
	global_load_dword v186, v[12:13], off
	global_load_dword v187, v[14:15], off
	s_branch .LBB0_478
.Lscan2_skip_refill:
	s_waitcnt vmcnt(0)
; __device__ __forceinline__ unsigned cvt_pk_bf16(float lo, float hi) { const bf16v2_t v = __builtin_convertvector((f32x2){lo, hi}, bf16v2_t); return __builtin_bit_cast(unsigned, v); }
; #define MFMA16(a, b, c) __builtin_amdgcn_mfma_f32_16x16x32_bf16(a, b, c, 0, 0, 0)
; #define SCAN_BAR() do { asm volatile("s_waitcnt lgkmcnt(0)" ::: "memory"); __builtin_amdgcn_s_barrier(); asm volatile("" ::: "memory"); } while (0)
; template <bool OUT> ...
;     ...
;         SCAN_BAR();
; #pragma unroll
;         for (int kt = 0; kt < 8; ++kt) S[kt] *= *(const f32x4*)(ER + 16 * kt + 4 * q);
;         f32x4 oacc[4];
;         if (OUT) {
;             bf16x8 Sb[4];
; #pragma unroll
;             for (int m = 0; m < 4; ++m) { u32x4 t; t.x = cvt_pk_bf16(S[2 * m][0], S[2 * m][1]); t.y = cvt_pk_bf16(S[2 * m][2], S[2 * m][3]); t.z = cvt_pk_bf16(S[2 * m + 1][0], S[2 * m + 1][1]); t.w = cvt_pk_bf16(S[2 * m + 1][2], S[2 * m + 1][3]);
;                 Sb[m] = __builtin_bit_cast(bf16x8, t); }
; #pragma unroll
;             for (int tb = 0; tb < 4; ++tb) { oacc[tb] = (f32x4){0.f, 0.f, 0.f, 0.f};
; #pragma unroll
;                 for (int m = 0; m < 4; ++m) { const unsigned char* qa = lds + L_QH + (16 * tb + fr) * 272 + (32 * m + 4 * q) * 2;
;                     const u32x2 lo = *(const u32x2*)qa, hi = *(const u32x2*)(qa + 32);
;                     const bf16x8 qf = __builtin_bit_cast(bf16x8, ((u32x4){lo.x, lo.y, hi.x, hi.y}));
;                     oacc[tb] = MFMA16(Sb[m], qf, oacc[tb]); } }
;             const int tb = w >> 1;
; #pragma unroll
;             for (int sbi = 0; sbi < 2; ++sbi) { const int sb = 2 * (w & 1) + sbi; f32x4 a = {0.f, 0.f, 0.f, 0.f};
;                 if (sb <= tb) {
; #pragma unroll
;                     for (int m = 0; m < 4; ++m) { const bf16x8 ka = *(const bf16x8*)(lds + L_KH + (16 * sb + fr) * 272 + (32 * m + 8 * q) * 2), qb = *(const bf16x8*)(lds + L_QH + (16 * tb + fr) * 272 + (32 * m + 8 * q) * 2);
;                         a = MFMA16(ka, qb, a); }
;                     const int tabs = 16 * tb + fr, s0 = 16 * sb + 4 * q;
; #pragma unroll
;                     for (int j = 0; j < 4; ++j) a[j] = (s0 + j <= tabs) ? a[j] : 0.f;
;                 }
;                 u32x2 wv; wv.x = cvt_pk_bf16(a[0], a[1]); wv.y = cvt_pk_bf16(a[2], a[3]);
;                 *(u32x2*)(lds + L_SC + (16 * tb + fr) * 144 + (16 * sb + 4 * q) * 2) = wv; }
.LBB0_478:
	s_waitcnt lgkmcnt(0)
	s_barrier
	v_add_u32_e32 v211, 0x14c00, v88
	ds_read_b128 v[0:3], v211
	ds_read_b128 v[4:7], v211 offset:64
	ds_read_b128 v[8:11], v211 offset:128
	ds_read_b128 v[12:15], v211 offset:192
	v_add_u32_e32 v213, 0x1000, v155
	s_waitcnt lgkmcnt(3)
	v_pk_mul_f32 v[2:3], v[18:19], v[2:3]
	s_waitcnt lgkmcnt(2)
	v_pk_mul_f32 v[6:7], v[16:17], v[6:7]
	ds_read_b128 v[16:19], v211 offset:256
	v_pk_mul_f32 v[0:1], v[20:21], v[0:1]
	v_pk_mul_f32 v[4:5], v[22:23], v[4:5]
	s_waitcnt lgkmcnt(2)
	v_pk_mul_f32 v[8:9], v[26:27], v[8:9]
	v_pk_mul_f32 v[10:11], v[24:25], v[10:11]
	ds_read_b128 v[20:23], v211 offset:320
	s_waitcnt lgkmcnt(1)
	v_pk_mul_f32 v[16:17], v[38:39], v[16:17]
	ds_read_b128 v[24:27], v211 offset:384
	v_pk_mul_f32 v[18:19], v[36:37], v[18:19]
	ds_read_b128 v[36:39], v211 offset:448
	v_pk_mul_f32 v[12:13], v[30:31], v[12:13]
	v_pk_mul_f32 v[14:15], v[28:29], v[14:15]
	s_waitcnt lgkmcnt(2)
	v_pk_mul_f32 v[28:29], v[32:33], v[20:21]
	v_pk_mul_f32 v[30:31], v[34:35], v[22:23]
	s_waitcnt lgkmcnt(1)
	v_pk_mul_f32 v[32:33], v[40:41], v[24:25]
	v_pk_mul_f32 v[34:35], v[42:43], v[26:27]
	s_waitcnt lgkmcnt(0)
	v_pk_mul_f32 v[24:25], v[46:47], v[36:37]
	v_pk_mul_f32 v[26:27], v[44:45], v[38:39]
	v_cvt_pk_bf16_f32 v44, v0, v1
	v_cvt_pk_bf16_f32 v45, v2, v3
	v_cvt_pk_bf16_f32 v46, v4, v5
	v_cvt_pk_bf16_f32 v47, v6, v7
	ds_read2_b64 v[20:23], v155 offset1:4
	v_cvt_pk_bf16_f32 v48, v8, v9
	v_cvt_pk_bf16_f32 v49, v10, v11
	v_cvt_pk_bf16_f32 v50, v12, v13
	v_cvt_pk_bf16_f32 v51, v14, v15
	ds_read2_b64 v[36:39], v155 offset0:8 offset1:12
	s_waitcnt lgkmcnt(1)
	v_mfma_f32_16x16x32_bf16 v[20:23], v[44:47], v[20:23], 0
	v_cvt_pk_bf16_f32 v52, v16, v17
	v_cvt_pk_bf16_f32 v53, v18, v19
	v_cvt_pk_bf16_f32 v54, v28, v29
	v_cvt_pk_bf16_f32 v55, v30, v31
	ds_read2_b64 v[40:43], v155 offset0:16 offset1:20
	s_waitcnt lgkmcnt(1)
	v_mfma_f32_16x16x32_bf16 v[20:23], v[48:51], v[36:39], v[20:23]
	v_cvt_pk_bf16_f32 v56, v32, v33
	v_cvt_pk_bf16_f32 v57, v34, v35
	v_cvt_pk_bf16_f32 v58, v24, v25
	v_cvt_pk_bf16_f32 v59, v26, v27
	ds_read2_b64 v[36:39], v155 offset0:24 offset1:28
	s_waitcnt lgkmcnt(1)
	v_mfma_f32_16x16x32_bf16 v[20:23], v[52:55], v[40:43], v[20:23]
	ds_read2_b64 v[40:43], v213 offset0:40 offset1:44
	v_add_u32_e32 v214, 0x2000, v155
	ds_read2_b64 v[60:63], v214 offset0:72 offset1:76
	s_waitcnt lgkmcnt(2)
	v_mfma_f32_16x16x32_bf16 v[20:23], v[56:59], v[36:39], v[20:23]
	ds_read2_b64 v[36:39], v213 offset0:32 offset1:36
	v_add_u32_e32 v215, 0x3000, v155
	s_lshr_b32 s3, s0, 7
	s_waitcnt lgkmcnt(0)
	v_mfma_f32_16x16x32_bf16 v[36:39], v[44:47], v[36:39], 0
	s_lshl_b32 s0, s20, 1
	s_and_b32 s20, s0, 2
	s_cmp_gt_u32 s20, s3
	v_mfma_f32_16x16x32_bf16 v[36:39], v[48:51], v[40:43], v[36:39]
	ds_read2_b64 v[40:43], v213 offset0:48 offset1:52
	s_waitcnt lgkmcnt(0)
	v_mfma_f32_16x16x32_bf16 v[36:39], v[52:55], v[40:43], v[36:39]
	ds_read2_b64 v[40:43], v213 offset0:56 offset1:60
	s_waitcnt lgkmcnt(0)
	v_mfma_f32_16x16x32_bf16 v[36:39], v[56:59], v[40:43], v[36:39]
	ds_read2_b64 v[40:43], v214 offset0:64 offset1:68
	s_waitcnt lgkmcnt(0)
	v_mfma_f32_16x16x32_bf16 v[40:43], v[44:47], v[40:43], 0
	v_mfma_f32_16x16x32_bf16 v[40:43], v[48:51], v[60:63], v[40:43]
	ds_read2_b64 v[60:63], v214 offset0:80 offset1:84
	s_waitcnt lgkmcnt(0)
	v_mfma_f32_16x16x32_bf16 v[40:43], v[52:55], v[60:63], v[40:43]
	ds_read2_b64 v[60:63], v214 offset0:88 offset1:92
	s_waitcnt lgkmcnt(0)
	v_mfma_f32_16x16x32_bf16 v[40:43], v[56:59], v[60:63], v[40:43]
	ds_read2_b64 v[60:63], v215 offset0:96 offset1:100
	s_waitcnt lgkmcnt(0)
	v_mfma_f32_16x16x32_bf16 v[44:47], v[44:47], v[60:63], 0
	ds_read2_b64 v[60:63], v215 offset0:104 offset1:108
	s_waitcnt lgkmcnt(0)
	v_mfma_f32_16x16x32_bf16 v[44:47], v[48:51], v[60:63], v[44:47]
	ds_read2_b64 v[48:51], v215 offset0:112 offset1:116
	s_waitcnt lgkmcnt(0)
	v_mfma_f32_16x16x32_bf16 v[44:47], v[52:55], v[48:51], v[44:47]
	ds_read2_b64 v[48:51], v215 offset0:120 offset1:124
	v_mov_b32_e32 v53, 0
	v_mov_b32_e32 v54, 0
	s_waitcnt lgkmcnt(0)
	v_mfma_f32_16x16x32_bf16 v[44:47], v[56:59], v[48:51], v[44:47]
	v_lshl_or_b32 v51, s3, 4, v81
	v_mul_lo_u32 v48, v51, s34
	v_add_u32_e32 v48, 0, v48
	v_mov_b32_e32 v50, 0
	v_add_u32_e32 v52, v48, v84
	v_mov_b32_e32 v55, 0
	v_mov_b32_e32 v56, 0
	s_cbranch_scc1 .LBB0_480
	s_lshl_b32 s0, s20, 4
	v_or_b32_e32 v48, s0, v81
	v_mad_u32_u24 v48, v48, s34, v88
	ds_read_b128 v[54:57], v48 offset:17408
	ds_read_b128 v[58:61], v48 offset:17472
	ds_read_b128 v[62:65], v52
	ds_read_b128 v[66:69], v52 offset:64
	s_waitcnt lgkmcnt(1)
	v_mfma_f32_16x16x32_bf16 v[54:57], v[54:57], v[62:65], 0
	ds_read_b128 v[62:65], v48 offset:17536
	ds_read_b128 v[70:73], v48 offset:17600
	v_or_b32_e32 v48, s0, v80
	v_cmp_le_u32_e32 vcc, v48, v51
	s_waitcnt lgkmcnt(2)
	v_mfma_f32_16x16x32_bf16 v[54:57], v[58:61], v[66:69], v[54:57]
	ds_read_b128 v[58:61], v52 offset:128
	ds_read_b128 v[66:69], v52 offset:192
	v_or_b32_e32 v49, 2, v48
	s_waitcnt lgkmcnt(1)
	v_mfma_f32_16x16x32_bf16 v[54:57], v[62:65], v[58:61], v[54:57]
	v_or_b32_e32 v58, 3, v48
	s_waitcnt lgkmcnt(0)
	v_mfma_f32_16x16x32_bf16 v[54:57], v[70:73], v[66:69], v[54:57]
	s_nop 7
	v_cndmask_b32_e32 v53, 0, v54, vcc
	v_cmp_lt_u32_e32 vcc, v48, v51
	s_nop 1
	v_cndmask_b32_e32 v54, 0, v55, vcc
	v_cmp_le_u32_e32 vcc, v49, v51
	s_nop 1
	v_cndmask_b32_e32 v55, 0, v56, vcc
	v_cmp_le_u32_e32 vcc, v58, v51
	s_nop 1
	v_cndmask_b32_e32 v56, 0, v57, vcc

; __device__ __forceinline__ unsigned cvt_pk_bf16(float lo, float hi) { const bf16v2_t v = __builtin_convertvector((f32x2){lo, hi}, bf16v2_t); return __builtin_bit_cast(unsigned, v); }
; #define MFMA16(a, b, c) __builtin_amdgcn_mfma_f32_16x16x32_bf16(a, b, c, 0, 0, 0)
; #define SCAN_BAR() do { asm volatile("s_waitcnt lgkmcnt(0)" ::: "memory"); __builtin_amdgcn_s_barrier(); asm volatile("" ::: "memory"); } while (0)
; template <bool OUT> ...
;     ...
;         f32x2 kf[8], loc[8]; f32x2 run = {1.f, 1.f};
; #pragma unroll
;         for (int j = 0; j < 8; ++j) { const h16x2 kk = __builtin_bit_cast(h16x2, gk[j]); kf[j] = (f32x2){(float)kk.x, (float)kk.y}; }
;         if (w >= 4) {
; #pragma unroll
;             for (int j = 0; j < 8; ++j) { run *= 1.f - kf[j]; loc[j] = run; }
;         } else {
; #pragma unroll
;             for (int j = 7; j >= 0; --j) { loc[j] = run; run *= 1.f - kf[j]; }
;         }
;     ...
;                 *(u32x2*)(lds + L_SC + (16 * tb + fr) * 144 + (16 * sb + 4 * q) * 2) = wv; }
;             SCAN_BAR();
;         }
;         bf16x8 Vf[2];
; #pragma unroll
;         for (int n = 0; n < 2; ++n) Vf[n] = *(const bf16x8*)(lds + L_VT + (16 * w + fr) * 144 + (32 * n + 8 * q) * 2);
;         if (OUT) {
; #pragma unroll
;             for (int tb = 0; tb < 4; ++tb) {
; #pragma unroll
;                 for (int n = 0; n < 2; ++n) { const bf16x8 sf = *(const bf16x8*)(lds + L_SC + (16 * tb + fr) * 144 + (32 * n + 8 * q) * 2); oacc[tb] = MFMA16(Vf[n], sf, oacc[tb]); }
;                 const size_t row = (size_t)(r0 + rs * (64 * c + 16 * tb + fr));
;                 u32x2 wv; wv.x = cvt_pk_bf16(oacc[tb][0], oacc[tb][1]); wv.y = cvt_pk_bf16(oacc[tb][2], oacc[tb][3]);
;                 *(u32x2*)(Op + row * 1024 + hcol + 16 * w + 4 * q) = wv; }
;         }
; #pragma unroll
;         for (int kt = 0; kt < 8; ++kt) {
; #pragma unroll
;             for (int n = 0; n < 2; ++n) { const bf16x8 kf = *(const bf16x8*)(lds + L_KHT + (16 * kt + fr) * 144 + (32 * n + 8 * q) * 2); S[kt] = MFMA16(kf, Vf[n], S[kt]); }
;             S[kt] *= *(const f32x4*)(EBR + 16 * kt + 4 * q); }
.LBB0_482:
	v_cvt_pk_bf16_f32 v50, v50, v49
	v_cvt_pk_bf16_f32 v51, v53, v54
	v_lshl_add_u32 v48, s0, 5, v48
	ds_write_b64 v48, v[50:51]
	v_or_b32_e32 v48, s2, v81
	s_waitcnt lgkmcnt(0)
	s_barrier
	v_mad_u64_u32 v[52:53], s[10:11], v48, s35, v[88:89]
	ds_read_b128 v[48:51], v52 offset:53248
	ds_read_b128 v[64:67], v52 offset:53312
	ds_read_b128 v[52:55], v156
	ds_read_b128 v[56:59], v156 offset:64
	s_waitcnt lgkmcnt(1)
	v_mfma_f32_16x16x32_bf16 v[20:23], v[48:51], v[52:55], v[20:23]
	v_add_u32_e32 v210, v88, v147
	v_add_u32_e32 v70, s70, v193
	s_lshl_b32 s0, s2, 1
	s_waitcnt lgkmcnt(0)
	v_mfma_f32_16x16x32_bf16 v[20:23], v[64:67], v[56:59], v[20:23]
	ds_read_b128 v[52:55], v156 offset:2304
	ds_read_b128 v[56:59], v156 offset:2368
	v_ashrrev_i32_e32 v71, 31, v70
	v_lshl_add_u64 v[68:69], v[112:113], 0, s[0:1]
	s_waitcnt lgkmcnt(1)
	v_mfma_f32_16x16x32_bf16 v[36:39], v[48:51], v[52:55], v[36:39]
	v_add_u32_e32 v212, 0x14e00, v88
	s_waitcnt vmcnt(24)
	v_cvt_f32_f16_sdwa v139, v172 dst_sel:DWORD dst_unused:UNUSED_PAD src0_sel:WORD_1
	v_cvt_f32_f16_e32 v138, v172
	s_waitcnt lgkmcnt(0)
	v_mfma_f32_16x16x32_bf16 v[36:39], v[64:67], v[56:59], v[36:39]
	ds_read_b128 v[52:55], v156 offset:4608
	ds_read_b128 v[56:59], v156 offset:4672
	v_cvt_f32_f16_sdwa v135, v175 dst_sel:DWORD dst_unused:UNUSED_PAD src0_sel:WORD_1
	v_cvt_f32_f16_e32 v134, v175
	s_waitcnt lgkmcnt(1)
	v_mfma_f32_16x16x32_bf16 v[40:43], v[48:51], v[52:55], v[40:43]
	v_cvt_f32_f16_sdwa v131, v178 dst_sel:DWORD dst_unused:UNUSED_PAD src0_sel:WORD_1
	v_cvt_f32_f16_e32 v130, v178
	v_cvt_f32_f16_sdwa v125, v195 dst_sel:DWORD dst_unused:UNUSED_PAD src0_sel:WORD_1
	s_waitcnt lgkmcnt(0)
	v_mfma_f32_16x16x32_bf16 v[40:43], v[64:67], v[56:59], v[40:43]
	ds_read_b128 v[52:55], v156 offset:6912
	ds_read_b128 v[56:59], v156 offset:6976
	v_cvt_f32_f16_e32 v124, v195
	v_cvt_f32_f16_sdwa v123, v198 dst_sel:DWORD dst_unused:UNUSED_PAD src0_sel:WORD_1
	s_waitcnt lgkmcnt(1)
	v_mfma_f32_16x16x32_bf16 v[44:47], v[48:51], v[52:55], v[44:47]
	ds_read_b128 v[52:55], v210 offset:34816
	ds_read_b128 v[60:63], v210 offset:34880
	v_cvt_pk_bf16_f32 v40, v40, v41
	v_cvt_pk_bf16_f32 v41, v42, v43
	s_waitcnt lgkmcnt(2)
	v_mfma_f32_16x16x32_bf16 v[44:47], v[64:67], v[56:59], v[44:47]
	ds_read_b128 v[56:59], v210 offset:37120
	v_cvt_f32_f16_e32 v122, v198
	v_cvt_f32_f16_sdwa v119, v201 dst_sel:DWORD dst_unused:UNUSED_PAD src0_sel:WORD_1
	s_waitcnt lgkmcnt(2)
	v_mfma_f32_16x16x32_bf16 v[0:3], v[52:55], v[48:51], v[0:3]
	ds_read_b128 v[52:55], v210 offset:37184
	v_cvt_f32_f16_e32 v118, v201
	v_cvt_f32_f16_sdwa v117, v204 dst_sel:DWORD dst_unused:UNUSED_PAD src0_sel:WORD_1
	s_waitcnt lgkmcnt(2)
	v_mfma_f32_16x16x32_bf16 v[0:3], v[60:63], v[64:67], v[0:3]
	v_cvt_pk_bf16_f32 v60, v20, v21
	v_cvt_pk_bf16_f32 v61, v22, v23
	ds_read_b128 v[20:23], v210 offset:39424
	s_waitcnt lgkmcnt(2)
	v_mfma_f32_16x16x32_bf16 v[4:7], v[56:59], v[48:51], v[4:7]
	v_lshlrev_b64 v[56:57], 11, v[70:71]
	v_lshl_add_u64 v[62:63], v[68:69], 0, v[56:57]
	ds_read_b128 v[56:59], v210 offset:39488
	s_waitcnt lgkmcnt(2)
	v_mfma_f32_16x16x32_bf16 v[4:7], v[52:55], v[64:67], v[4:7]
	ds_read_b128 v[52:55], v210 offset:41728
	global_store_dwordx2 v[62:63], v[60:61], off
	v_add_u32_e32 v60, s70, v190
	s_waitcnt lgkmcnt(2)
	v_mfma_f32_16x16x32_bf16 v[8:11], v[20:23], v[48:51], v[8:11]
	v_cvt_pk_bf16_f32 v62, v36, v37
	v_cvt_pk_bf16_f32 v63, v38, v39
	ds_read_b128 v[36:39], v210 offset:44032
	v_ashrrev_i32_e32 v61, 31, v60
	s_waitcnt lgkmcnt(2)
	v_mfma_f32_16x16x32_bf16 v[8:11], v[56:59], v[64:67], v[8:11]
	v_lshlrev_b64 v[56:57], 11, v[60:61]
	ds_read_b128 v[20:23], v210 offset:41792
	v_add_u32_e32 v60, s70, v191
	s_waitcnt lgkmcnt(2)
	v_mfma_f32_16x16x32_bf16 v[12:15], v[52:55], v[48:51], v[12:15]
	v_lshl_add_u64 v[52:53], v[68:69], 0, v[56:57]
	global_store_dwordx2 v[52:53], v[62:63], off
	ds_read_b128 v[52:55], v210 offset:44096
	s_waitcnt lgkmcnt(2)
	v_mfma_f32_16x16x32_bf16 v[16:19], v[36:39], v[48:51], v[16:19]
	v_ashrrev_i32_e32 v61, 31, v60
	ds_read_b128 v[56:59], v210 offset:46336
	ds_read_b128 v[36:39], v210 offset:46400
	s_waitcnt lgkmcnt(3)
	v_mfma_f32_16x16x32_bf16 v[12:15], v[20:23], v[64:67], v[12:15]
	v_cvt_f32_f16_e32 v116, v204
	v_cvt_f32_f16_sdwa v115, v207 dst_sel:DWORD dst_unused:UNUSED_PAD src0_sel:WORD_1
	v_cvt_f32_f16_e32 v114, v207
	s_waitcnt lgkmcnt(2)
	v_mfma_f32_16x16x32_bf16 v[20:23], v[52:55], v[64:67], v[16:19]
	v_add_u32_e32 v52, s70, v192
	v_ashrrev_i32_e32 v53, 31, v52
	v_readfirstlane_b32 s0, v242
	v_lshlrev_b64 v[16:17], 11, v[60:61]
	v_lshl_add_u64 v[42:43], v[68:69], 0, v[16:17]
	ds_read_b128 v[16:19], v210 offset:48640
	s_waitcnt lgkmcnt(2)
	v_mfma_f32_16x16x32_bf16 v[28:31], v[56:59], v[48:51], v[28:31]
	global_store_dwordx2 v[42:43], v[40:41], off
	ds_read_b128 v[40:43], v210 offset:48704
	s_cmpk_gt_u32 s0, 0xff
	s_waitcnt lgkmcnt(1)
	v_mfma_f32_16x16x32_bf16 v[16:19], v[16:19], v[48:51], v[32:35]
	s_nop 2
	ds_read_b128 v[32:35], v210 offset:50944
	s_cselect_b64 s[2:3], -1, 0
	s_mov_b64 s[20:21], -1
	v_mfma_f32_16x16x32_bf16 v[28:31], v[36:39], v[64:67], v[28:31]
	v_lshlrev_b64 v[38:39], 11, v[52:53]
	v_cvt_pk_bf16_f32 v36, v44, v45
	v_cvt_pk_bf16_f32 v37, v46, v47
	v_lshl_add_u64 v[38:39], v[68:69], 0, v[38:39]
	global_store_dwordx2 v[38:39], v[36:37], off
	ds_read_b128 v[36:39], v210 offset:51008
	s_waitcnt lgkmcnt(1)
	v_mfma_f32_16x16x32_bf16 v[24:27], v[32:35], v[48:51], v[24:27]
	ds_read_b128 v[60:63], v212
	ds_read_b128 v[56:59], v212 offset:64
	s_and_b64 vcc, exec, s[2:3]
	v_pk_add_f32 v[120:121], v[114:115], 1.0 op_sel_hi:[1,0] neg_lo:[1,0] neg_hi:[1,0]
	v_mfma_f32_16x16x32_bf16 v[16:19], v[40:43], v[64:67], v[16:19]
	ds_read_b128 v[52:55], v212 offset:128
	ds_read_b128 v[48:51], v212 offset:192
	ds_read_b128 v[44:47], v212 offset:256
	ds_read_b128 v[40:43], v212 offset:320
	v_pk_add_f32 v[68:69], v[118:119], 1.0 op_sel_hi:[1,0] neg_lo:[1,0] neg_hi:[1,0]
	v_pk_add_f32 v[72:73], v[122:123], 1.0 op_sel_hi:[1,0] neg_lo:[1,0] neg_hi:[1,0]
	s_waitcnt lgkmcnt(6)
	v_mfma_f32_16x16x32_bf16 v[24:27], v[36:39], v[64:67], v[24:27]
	ds_read_b128 v[36:39], v212 offset:384
	ds_read_b128 v[32:35], v212 offset:448
	v_pk_add_f32 v[66:67], v[116:117], 1.0 op_sel_hi:[1,0] neg_lo:[1,0] neg_hi:[1,0]
	v_pk_add_f32 v[74:75], v[124:125], 1.0 op_sel_hi:[1,0] neg_lo:[1,0] neg_hi:[1,0]
	v_pk_add_f32 v[76:77], v[130:131], 1.0 op_sel_hi:[1,0] neg_lo:[1,0] neg_hi:[1,0]
	v_pk_add_f32 v[78:79], v[134:135], 1.0 op_sel_hi:[1,0] neg_lo:[1,0] neg_hi:[1,0]
	v_pk_add_f32 v[70:71], v[138:139], 1.0 op_sel_hi:[1,0] neg_lo:[1,0] neg_hi:[1,0]
	s_cbranch_vccnz .LBB0_484
	v_pk_mul_f32 v[126:127], v[120:121], v[66:67]
	v_pk_add_f32 v[64:65], v[138:139], 1.0 op_sel_hi:[1,0] neg_lo:[1,0] neg_hi:[1,0]
	v_pk_mul_f32 v[132:133], v[68:69], v[126:127]
	s_mov_b64 s[20:21], 0
	v_pk_mul_f32 v[136:137], v[72:73], v[132:133]
	s_nop 0
	v_pk_mul_f32 v[140:141], v[74:75], v[136:137]
	s_nop 0
	v_pk_mul_f32 v[142:143], v[76:77], v[140:141]
	s_nop 0
	v_pk_mul_f32 v[144:145], v[78:79], v[142:143]
	s_nop 0
	v_pk_mul_f32 v[64:65], v[64:65], v[144:145]
